# v114 + attention-loop trim: the four s_nop after m0 writes removed by reordering the DMA address SALU (one target via a spare SGPR)
# speedup vs baseline: 1.0028x; 1.0027x over previous
; #define LAS __attribute__((address_space(3)))
; __device__ __forceinline__ int v_rd_base(int lane) { return ((lane & 3) << 3) | (((lane >> 2) & 3) << 6) | (((lane >> 4) & 1) << 5) | (((lane >> 5) & 1) << 8); }
; template <bool SAFE>
; __device__ __forceinline__ bool attn_unit_prompt_t(LAS unsigned char* lds, const bf16* Kg, const bf16* Vg, const bf16* Qrow0, bf16* Orow0, int NT, int qpos0, int h, const float* gnorm) {
;     ...
;   const LAS char* vrd = V_lds + v_rd_base(lane);
.Lmy533:
	s_mov_b32 s37, s64
	s_add_i32 s32, s37, 0
	s_waitcnt vmcnt(4)
	s_barrier
	v_add_u32_e32 v161, s32, v9
	v_add_u32_e32 v211, s32, v10
	ds_read_b128 v[4:7], v161
	ds_read_b128 v[14:17], v161 offset:8192
	s_mov_b32 s64, s8
	s_and_b32 s66, s36, 0xc000
	v_add_u32_e32 v147, s66, v194
	s_add_i32 s67, s36, 0x4000
	s_and_b32 s67, s67, 0xc000
	v_add_u32_e32 v160, s67, v194
	s_waitcnt lgkmcnt(10)
	v_mfma_f32_32x32x16_bf16 v[66:81], v[130:133], v[246:249], v[66:81]
	v_exp_f32_e32 v98, v98
	ds_read_b64_tr_b16 v[246:247], v147 offset:57344
	ds_read_b64_tr_b16 v[248:249], v147 offset:59392
	ds_read_b128 v[148:151], v211
	v_mfma_f32_32x32x16_bf16 v[50:65], v[130:133], v[250:253], v[50:65]
	v_exp_f32_e32 v99, v99
	ds_read_b64_tr_b16 v[250:251], v147 offset:57856
	ds_read_b64_tr_b16 v[252:253], v147 offset:59904
	ds_read_b128 v[152:155], v211 offset:8192
	v_mfma_f32_32x32x16_bf16 v[34:49], v[130:133], v[198:201], v[34:49]
	v_exp_f32_e32 v100, v100
	ds_read_b64_tr_b16 v[198:199], v147 offset:58368
	ds_read_b64_tr_b16 v[200:201], v147 offset:60416
	v_add_u32_e32 v161, s32, v11
	v_add_u32_e32 v211, s32, v12
	v_mfma_f32_32x32x16_bf16 v[18:33], v[130:133], v[202:205], v[18:33]
	v_exp_f32_e32 v101, v101
	v_exp_f32_e32 v102, v102
	ds_read_b64_tr_b16 v[202:203], v147 offset:58880
	ds_read_b64_tr_b16 v[204:205], v147 offset:60928
	v_mfma_f32_16x16x32_bf16 v[182:185], v[130:133], v[162:165], v[182:185]
	ds_read_b128 v[156:159], v161
	ds_read_b128 v[186:189], v161 offset:8192
	s_waitcnt lgkmcnt(14)
	v_mfma_f32_32x32x16_bf16 v[66:81], v[134:137], v[206:209], v[66:81]
	v_exp_f32_e32 v103, v103
	ds_read_b64_tr_b16 v[206:207], v147 offset:61440
	ds_read_b64_tr_b16 v[208:209], v147 offset:63488
	ds_read_b128 v[224:227], v211
	v_mfma_f32_32x32x16_bf16 v[50:65], v[134:137], v[236:239], v[50:65]
	v_exp_f32_e32 v104, v104
	ds_read_b64_tr_b16 v[236:237], v147 offset:61952
	ds_read_b64_tr_b16 v[238:239], v147 offset:64000
	ds_read_b128 v[228:231], v211 offset:8192
	v_mfma_f32_32x32x16_bf16 v[34:49], v[134:137], v[240:243], v[34:49]
	v_exp_f32_e32 v105, v105
	v_exp_f32_e32 v106, v106
	ds_read_b64_tr_b16 v[240:241], v147 offset:62464
	ds_read_b64_tr_b16 v[242:243], v147 offset:64512
	v_mfma_f32_32x32x16_bf16 v[18:33], v[134:137], v[232:235], v[18:33]
	v_exp_f32_e32 v107, v107
	v_exp_f32_e32 v108, v108
	ds_read_b64_tr_b16 v[232:233], v147 offset:62976
	ds_read_b64_tr_b16 v[234:235], v147 offset:65024
	v_mfma_f32_16x16x32_bf16 v[182:185], v[134:137], v[162:165], v[182:185]
	s_add_u32 s48, s0, s12
	s_addc_u32 s54, s1, s13
	s_add_u32 s8, s48, 0x138000
	s_addc_u32 s9, s54, 0
	s_add_i32 s15, s64, s30
	s_mov_b32 m0, s15
	s_add_u32 s55, s21, s12
	s_addc_u32 s93, s34, s13
	global_load_lds_dwordx4 v214, s[8:9] offset:0
	global_load_lds_dwordx4 v215, s[8:9] offset:1024
	s_waitcnt lgkmcnt(14)
	v_mfma_f32_32x32x16_bf16 v[130:145], v[4:7], v[178:181], v[82:97]
	s_add_i32 s15, s36, 0xffffc000
	s_and_b32 s15, s15, 0xc000
	s_add_i32 s15, s15, s31
	s_mov_b32 m0, s15
	s_add_u32 s8, s55, 0xcf39200
	s_addc_u32 s9, s93, 0
	global_load_lds_dwordx4 v216, s[8:9] offset:0
	global_load_lds_dwordx4 v217, s[8:9] offset:1024
	v_mfma_f32_32x32x16_bf16 v[130:145], v[148:151], v[174:177], v[130:145]
	v_exp_f32_e32 v109, v109
	v_exp_f32_e32 v110, v110
	s_waitcnt lgkmcnt(4)
	v_mfma_f32_32x32x16_bf16 v[130:145], v[156:159], v[170:173], v[130:145]
	v_exp_f32_e32 v111, v111
	v_exp_f32_e32 v112, v112
	v_mfma_f32_32x32x16_bf16 v[130:145], v[224:227], v[166:169], v[130:145]
	v_exp_f32_e32 v113, v113
	v_mfma_f32_32x32x16_bf16 v[114:129], v[14:17], v[178:181], v[82:97]
	v_cvt_pk_bf16_f32 v98, v98, v99
	v_cvt_pk_bf16_f32 v99, v100, v101
	v_mfma_f32_32x32x16_bf16 v[114:129], v[152:155], v[174:177], v[114:129]
	v_cvt_pk_bf16_f32 v100, v102, v103
	v_cvt_pk_bf16_f32 v101, v104, v105
	v_mfma_f32_32x32x16_bf16 v[114:129], v[186:189], v[170:173], v[114:129]
	v_cvt_pk_bf16_f32 v102, v106, v107
	v_cvt_pk_bf16_f32 v103, v108, v109
	v_mfma_f32_32x32x16_bf16 v[114:129], v[228:231], v[166:169], v[114:129]
	v_cvt_pk_bf16_f32 v104, v110, v111
	v_cvt_pk_bf16_f32 v105, v112, v113
	s_waitcnt lgkmcnt(12)
	v_mfma_f32_32x32x16_bf16 v[66:81], v[98:101], v[246:249], v[66:81]
	v_exp_f32_e32 v130, v130
	v_exp_f32_e32 v131, v131
	ds_read_b64_tr_b16 v[246:247], v160 offset:49152
	ds_read_b64_tr_b16 v[248:249], v160 offset:51200
	v_mfma_f32_32x32x16_bf16 v[50:65], v[98:101], v[250:253], v[50:65]
	v_exp_f32_e32 v132, v132
	v_exp_f32_e32 v133, v133
	ds_read_b64_tr_b16 v[250:251], v160 offset:49664
	ds_read_b64_tr_b16 v[252:253], v160 offset:51712
	v_mfma_f32_32x32x16_bf16 v[34:49], v[98:101], v[198:201], v[34:49]
	v_exp_f32_e32 v134, v134
	v_exp_f32_e32 v135, v135
	ds_read_b64_tr_b16 v[198:199], v160 offset:50176
	ds_read_b64_tr_b16 v[200:201], v160 offset:52224
	v_mfma_f32_32x32x16_bf16 v[18:33], v[98:101], v[202:205], v[18:33]
	v_exp_f32_e32 v136, v136
	v_exp_f32_e32 v137, v137
	ds_read_b64_tr_b16 v[202:203], v160 offset:50688
	ds_read_b64_tr_b16 v[204:205], v160 offset:52736
	v_mfma_f32_16x16x32_bf16 v[182:185], v[98:101], v[162:165], v[182:185]
	v_exp_f32_e32 v138, v138
	v_exp_f32_e32 v139, v139
	s_waitcnt lgkmcnt(8)
	v_mfma_f32_32x32x16_bf16 v[66:81], v[102:105], v[206:209], v[66:81]
	v_exp_f32_e32 v140, v140
	v_exp_f32_e32 v141, v141
	ds_read_b64_tr_b16 v[206:207], v160 offset:53248
	ds_read_b64_tr_b16 v[208:209], v160 offset:55296
	v_mfma_f32_32x32x16_bf16 v[50:65], v[102:105], v[236:239], v[50:65]
	v_exp_f32_e32 v142, v142
	v_exp_f32_e32 v143, v143
	ds_read_b64_tr_b16 v[236:237], v160 offset:53760
	ds_read_b64_tr_b16 v[238:239], v160 offset:55808
	v_mfma_f32_32x32x16_bf16 v[34:49], v[102:105], v[240:243], v[34:49]
	v_exp_f32_e32 v144, v144
	v_exp_f32_e32 v145, v145
	ds_read_b64_tr_b16 v[240:241], v160 offset:54272
	ds_read_b64_tr_b16 v[242:243], v160 offset:56320
	v_mfma_f32_32x32x16_bf16 v[18:33], v[102:105], v[232:235], v[18:33]
	v_cvt_pk_bf16_f32 v130, v130, v131
	v_cvt_pk_bf16_f32 v131, v132, v133
	v_cvt_pk_bf16_f32 v132, v134, v135
	v_cvt_pk_bf16_f32 v133, v136, v137
	ds_read_b64_tr_b16 v[232:233], v160 offset:54784
	ds_read_b64_tr_b16 v[234:235], v160 offset:56832
	v_mfma_f32_16x16x32_bf16 v[182:185], v[102:105], v[162:165], v[182:185]
	v_cvt_pk_bf16_f32 v134, v138, v139
	v_cvt_pk_bf16_f32 v135, v140, v141
	v_cvt_pk_bf16_f32 v136, v142, v143
	v_cvt_pk_bf16_f32 v137, v144, v145
	s_add_i32 s32, s65, 0
	s_waitcnt vmcnt(4)
	s_barrier
; #define LAS __attribute__((address_space(3)))
; __device__ __forceinline__ int v_rd_base(int lane) { return ((lane & 3) << 3) | (((lane >> 2) & 3) << 6) | (((lane >> 4) & 1) << 5) | (((lane >> 5) & 1) << 8); }
; template <bool SAFE>
; __device__ __forceinline__ bool attn_unit_prompt_t(LAS unsigned char* lds, const bf16* Kg, const bf16* Vg, const bf16* Qrow0, bf16* Orow0, int NT, int qpos0, int h, const float* gnorm) {
;     ...
;   const LAS char* vrd = V_lds + v_rd_base(lane);
;     ...
;   for (; j + 1 < NT - 4; j += 2) { HALFSTEP(pB0, pB1, pA0, pA1, alB, j, false); HALFSTEP(pA0, pA1, pB0, pB1, alA, j + 1, false); }
	v_add_u32_e32 v161, s32, v9
	v_add_u32_e32 v211, s32, v10
	ds_read_b128 v[4:7], v161
	ds_read_b128 v[14:17], v161 offset:8192
	s_add_i32 s67, s36, 0x8000
	s_and_b32 s67, s67, 0xc000
	v_add_u32_e32 v147, s67, v194
	s_waitcnt lgkmcnt(10)
	v_mfma_f32_32x32x16_bf16 v[66:81], v[130:133], v[246:249], v[66:81]
	v_exp_f32_e32 v114, v114
	ds_read_b64_tr_b16 v[246:247], v160 offset:57344
	ds_read_b64_tr_b16 v[248:249], v160 offset:59392
	ds_read_b128 v[148:151], v211
	v_mfma_f32_32x32x16_bf16 v[50:65], v[130:133], v[250:253], v[50:65]
	v_exp_f32_e32 v115, v115
	ds_read_b64_tr_b16 v[250:251], v160 offset:57856
	ds_read_b64_tr_b16 v[252:253], v160 offset:59904
	ds_read_b128 v[152:155], v211 offset:8192
	v_mfma_f32_32x32x16_bf16 v[34:49], v[130:133], v[198:201], v[34:49]
	v_exp_f32_e32 v116, v116
	ds_read_b64_tr_b16 v[198:199], v160 offset:58368
	ds_read_b64_tr_b16 v[200:201], v160 offset:60416
	v_add_u32_e32 v161, s32, v11
	v_add_u32_e32 v211, s32, v12
	v_mfma_f32_32x32x16_bf16 v[18:33], v[130:133], v[202:205], v[18:33]
	v_exp_f32_e32 v117, v117
	v_exp_f32_e32 v118, v118
	ds_read_b64_tr_b16 v[202:203], v160 offset:58880
	ds_read_b64_tr_b16 v[204:205], v160 offset:60928
	v_mfma_f32_16x16x32_bf16 v[182:185], v[130:133], v[162:165], v[182:185]
	ds_read_b128 v[156:159], v161
	ds_read_b128 v[186:189], v161 offset:8192
	s_waitcnt lgkmcnt(14)
	v_mfma_f32_32x32x16_bf16 v[66:81], v[134:137], v[206:209], v[66:81]
	v_exp_f32_e32 v119, v119
	ds_read_b64_tr_b16 v[206:207], v160 offset:61440
	ds_read_b64_tr_b16 v[208:209], v160 offset:63488
	ds_read_b128 v[224:227], v211
	v_mfma_f32_32x32x16_bf16 v[50:65], v[134:137], v[236:239], v[50:65]
	v_exp_f32_e32 v120, v120
	ds_read_b64_tr_b16 v[236:237], v160 offset:61952
	ds_read_b64_tr_b16 v[238:239], v160 offset:64000
	ds_read_b128 v[228:231], v211 offset:8192
	v_mfma_f32_32x32x16_bf16 v[34:49], v[134:137], v[240:243], v[34:49]
	v_exp_f32_e32 v121, v121
	v_exp_f32_e32 v122, v122
	ds_read_b64_tr_b16 v[240:241], v160 offset:62464
	ds_read_b64_tr_b16 v[242:243], v160 offset:64512
	v_mfma_f32_32x32x16_bf16 v[18:33], v[134:137], v[232:235], v[18:33]
	v_exp_f32_e32 v123, v123
	v_exp_f32_e32 v124, v124
	ds_read_b64_tr_b16 v[232:233], v160 offset:62976
	ds_read_b64_tr_b16 v[234:235], v160 offset:65024
	v_mfma_f32_16x16x32_bf16 v[182:185], v[134:137], v[162:165], v[182:185]
	s_add_i32 s99, s37, s30
	s_mov_b32 m0, s99
	s_add_u32 s14, s48, 0x1a0000
	s_addc_u32 s15, s54, 0
	global_load_lds_dwordx4 v214, s[14:15] offset:0
	global_load_lds_dwordx4 v215, s[14:15] offset:1024
	s_waitcnt lgkmcnt(14)
	v_mfma_f32_32x32x16_bf16 v[130:145], v[4:7], v[178:181], v[82:97]
	s_add_i32 s48, s66, s31
	s_mov_b32 m0, s48
	s_add_u32 s14, s55, 0xcfa1200
	s_addc_u32 s15, s93, 0
	global_load_lds_dwordx4 v216, s[14:15] offset:0
	global_load_lds_dwordx4 v217, s[14:15] offset:1024
	v_mfma_f32_32x32x16_bf16 v[130:145], v[148:151], v[174:177], v[130:145]
	v_exp_f32_e32 v125, v125
	v_exp_f32_e32 v126, v126
	s_waitcnt lgkmcnt(4)
	v_mfma_f32_32x32x16_bf16 v[130:145], v[156:159], v[170:173], v[130:145]
	v_exp_f32_e32 v127, v127
	v_exp_f32_e32 v128, v128
	v_mfma_f32_32x32x16_bf16 v[130:145], v[224:227], v[166:169], v[130:145]
	v_exp_f32_e32 v129, v129
	v_mfma_f32_32x32x16_bf16 v[98:113], v[14:17], v[178:181], v[82:97]
	v_cvt_pk_bf16_f32 v114, v114, v115
	v_cvt_pk_bf16_f32 v115, v116, v117
	v_mfma_f32_32x32x16_bf16 v[98:113], v[152:155], v[174:177], v[98:113]
	v_cvt_pk_bf16_f32 v116, v118, v119
	v_cvt_pk_bf16_f32 v117, v120, v121
	v_mfma_f32_32x32x16_bf16 v[98:113], v[186:189], v[170:173], v[98:113]
	v_cvt_pk_bf16_f32 v118, v122, v123
	v_cvt_pk_bf16_f32 v119, v124, v125
	v_mfma_f32_32x32x16_bf16 v[98:113], v[228:231], v[166:169], v[98:113]
	v_cvt_pk_bf16_f32 v120, v126, v127
	v_cvt_pk_bf16_f32 v121, v128, v129
	s_waitcnt lgkmcnt(12)
	v_mfma_f32_32x32x16_bf16 v[66:81], v[114:117], v[246:249], v[66:81]
	v_exp_f32_e32 v130, v130
	v_exp_f32_e32 v131, v131
	ds_read_b64_tr_b16 v[246:247], v147 offset:49152
	ds_read_b64_tr_b16 v[248:249], v147 offset:51200
	v_mfma_f32_32x32x16_bf16 v[50:65], v[114:117], v[250:253], v[50:65]
	v_exp_f32_e32 v132, v132
	v_exp_f32_e32 v133, v133
	ds_read_b64_tr_b16 v[250:251], v147 offset:49664
	ds_read_b64_tr_b16 v[252:253], v147 offset:51712
	v_mfma_f32_32x32x16_bf16 v[34:49], v[114:117], v[198:201], v[34:49]
	v_exp_f32_e32 v134, v134
	v_exp_f32_e32 v135, v135
	ds_read_b64_tr_b16 v[198:199], v147 offset:50176
	ds_read_b64_tr_b16 v[200:201], v147 offset:52224
	v_mfma_f32_32x32x16_bf16 v[18:33], v[114:117], v[202:205], v[18:33]
	v_exp_f32_e32 v136, v136
	v_exp_f32_e32 v137, v137
	ds_read_b64_tr_b16 v[202:203], v147 offset:50688
	ds_read_b64_tr_b16 v[204:205], v147 offset:52736
	v_mfma_f32_16x16x32_bf16 v[182:185], v[114:117], v[162:165], v[182:185]
	v_exp_f32_e32 v138, v138
	v_exp_f32_e32 v139, v139
	s_waitcnt lgkmcnt(8)
	v_mfma_f32_32x32x16_bf16 v[66:81], v[118:121], v[206:209], v[66:81]
	v_exp_f32_e32 v140, v140
	v_exp_f32_e32 v141, v141
	ds_read_b64_tr_b16 v[206:207], v147 offset:53248
	ds_read_b64_tr_b16 v[208:209], v147 offset:55296
	v_mfma_f32_32x32x16_bf16 v[50:65], v[118:121], v[236:239], v[50:65]
	v_exp_f32_e32 v142, v142
	v_exp_f32_e32 v143, v143
	ds_read_b64_tr_b16 v[236:237], v147 offset:53760
	ds_read_b64_tr_b16 v[238:239], v147 offset:55808
	v_mfma_f32_32x32x16_bf16 v[34:49], v[118:121], v[240:243], v[34:49]
	v_exp_f32_e32 v144, v144
	v_exp_f32_e32 v145, v145
	ds_read_b64_tr_b16 v[240:241], v147 offset:54272
	ds_read_b64_tr_b16 v[242:243], v147 offset:56320
	v_mfma_f32_32x32x16_bf16 v[18:33], v[118:121], v[232:235], v[18:33]
	v_cvt_pk_bf16_f32 v130, v130, v131
	v_cvt_pk_bf16_f32 v131, v132, v133
	v_cvt_pk_bf16_f32 v132, v134, v135
	v_cvt_pk_bf16_f32 v133, v136, v137
	ds_read_b64_tr_b16 v[232:233], v147 offset:54784
	ds_read_b64_tr_b16 v[234:235], v147 offset:56832
	v_mfma_f32_16x16x32_bf16 v[182:185], v[118:121], v[162:165], v[182:185]
	v_cvt_pk_bf16_f32 v134, v138, v139
	v_cvt_pk_bf16_f32 v135, v140, v141
	v_cvt_pk_bf16_f32 v136, v142, v143
	v_cvt_pk_bf16_f32 v137, v144, v145
	s_add_i32 s35, s35, 2
	s_add_i32 s36, s36, 0x8000
	s_add_u32 s12, s12, 0xd0000
	s_addc_u32 s13, s13, 0
	s_cmp_ge_i32 s35, s20
	s_cbranch_scc1 .Lmy533_exit
	s_mov_b32 s8, s65
	s_mov_b32 s65, s37
	s_branch .Lmy533
